# gate|up: no accumulator clearing; first K-iteration peeled with C = 0 in each accumulator's first MFMA
# speedup vs baseline: 1.0075x; 1.0052x over previous
; #define PG8_STAGE(bufoff, gbase, voff) do { _Pragma("unroll") for (int _i = 0; _i < 2; ++_i) \
;         __builtin_amdgcn_global_load_lds((const unsigned*)((const char*)(gbase) + (voff)[_i]), (PG8_LAS unsigned*)(lds + (bufoff) + ldsw + _i * 8192), 16, 0, 0); } while (0)
; #define PG8_STAGEA(bufoff, gbase, voff) do { _Pragma("unroll") for (int _i = 0; _i < 2; ++_i) \
;         __builtin_amdgcn_global_load_lds((const unsigned*)((const char*)(gbase) + (voff)[_i]), (PG8_LAS unsigned*)(lds + (bufoff) + ldsw + _i * 8192), 16, 0, A_AUX); } while (0)
; #define PG8_LDA(dst, b, h) do { _Pragma("unroll") for (int m = 0; m < 4; ++m) _Pragma("unroll") for (int k = 0; k < 2; ++k) dst[m][k] = *(const PG8_LAS bf16x8*)(lds + PG8_SA(b, h) + aoff + m * 2048 + k * 1024); } while (0)
; #define PG8_LDB(dst, b, h) do { _Pragma("unroll") for (int n = 0; n < 2; ++n) _Pragma("unroll") for (int k = 0; k < 2; ++k) dst[n][k] = *(const PG8_LAS bf16x8*)(lds + PG8_SB(b, h) + boff + n * 2048 + k * 1024); } while (0)
; #define PG8_MMA(ai, bj, At, Bt) do { __builtin_amdgcn_s_setprio(1); _Pragma("unroll") for (int m = 0; m < 4; ++m) _Pragma("unroll") for (int n = 0; n < 2; ++n) _Pragma("unroll") for (int k = 0; k < 2; ++k) \
;         acc[ai][bj][m][n] = __builtin_amdgcn_mfma_f32_16x16x32_bf16(Bt[n][k], At[m][k], acc[ai][bj][m][n], 0, 0, 0); __builtin_amdgcn_s_setprio(0); } while (0)
; #define PG8_WAIT_V(n) asm volatile("s_waitcnt vmcnt(" #n ")" ::: "memory")
; #define PG8_WAIT_L(n) asm volatile("s_waitcnt lgkmcnt(" #n ")" ::: "memory")
; #define PG8_BAR __builtin_amdgcn_s_barrier()
;     ...
; #pragma unroll
;     for (int a = 0; a < 2; ++a)
; #pragma unroll
;         for (int b = 0; b < 2; ++b)
; #pragma unroll
;             for (int m = 0; m < 4; ++m)
; #pragma unroll
;                 for (int n = 0; n < 2; ++n) acc[a][b][m][n] = (f32x4){0.f, 0.f, 0.f, 0.f};
;     ...
;             PG8_LDB(B0, 0, 0); PG8_LDB(B1, 0, 1); PG8_SCHED; PG8_LDA(At, 0, 0); PG8_STAGEA(PG8_SA(1, 1), a1 + hstep, voffA);
;             PG8_WAIT_V(8); PG8_WAIT_L(0); PG8_BAR; PG8_MMA(0, 0, At, B0); PG8_MMA(0, 1, At, B1); PG8_BAR; PG8_SCHED;
;             PG8_LDA(At, 0, 1); PG8_STAGE(PG8_SB(0, 0), b2, voffB); PG8_STAGE(PG8_SB(0, 1), b2 + hstep, voffB); PG8_STAGEA(PG8_SA(0, 0), a2, voffA);
;             PG8_WAIT_V(8); PG8_WAIT_L(0); PG8_BAR; PG8_MMA(1, 0, At, B0); PG8_MMA(1, 1, At, B1); PG8_BAR; PG8_SCHED;
.LBB0_579:
	s_ashr_i32 s45, s44, 31
	s_lshl_b64 s[16:17], s[44:45], 19
	s_add_u32 s46, s97, s16
	s_addc_u32 s47, s29, s17
	s_and_b64 s[16:17], s[40:41], exec
	s_cselect_b32 s16, s47, s51
	s_cselect_b32 s17, s46, s50
	s_ashr_i32 s43, s42, 31
	s_lshl_b64 s[48:49], s[42:43], 19
	s_add_u32 s48, s23, s48
	s_addc_u32 s49, s56, s49
	s_and_b64 s[54:55], s[40:41], exec
	s_cselect_b32 s43, s49, s53
	s_cselect_b32 s45, s48, s52
	s_add_u32 s50, s50, 0x40080
	s_addc_u32 s51, s51, 0
	s_add_u32 s73, s52, 0x100
	s_addc_u32 s76, s53, 0
	s_mov_b32 vcc_lo, -2
	s_add_u32 s52, s50, 0xfffc0080
	s_addc_u32 s53, s51, -1
	s_add_i32 s70, 0, 0x10000
	s_cmp_eq_u32 vcc_lo, 12
	s_cselect_b32 s55, s16, s53
	s_cselect_b32 s54, s17, s52
	v_add_u32_e32 v140, s70, v143
	s_cselect_b32 s53, s43, s76
	s_cselect_b32 s52, s45, s73
	s_add_i32 vcc_hi, 0, 0x14000
	ds_read_b128 v[146:149], v140
	ds_read_b128 v[150:153], v140 offset:1024
	ds_read_b128 v[154:157], v140 offset:2048
	ds_read_b128 v[158:161], v140 offset:3072
	v_add_u32_e32 v140, vcc_hi, v143
	ds_read_b128 v[174:177], v140
	ds_read_b128 v[178:181], v140 offset:1024
	ds_read_b128 v[182:185], v140 offset:2048
	ds_read_b128 v[186:189], v140 offset:3072
	v_lshl_add_u64 v[140:141], s[50:51], 0, v[136:137]
	s_add_i32 m0, s58, 0xc000
	ds_read_b128 v[200:203], v145
	ds_read_b128 v[208:211], v145 offset:1024
	ds_read_b128 v[212:215], v145 offset:2048
	ds_read_b128 v[216:219], v145 offset:3072
	ds_read_b128 v[220:223], v145 offset:4096
	ds_read_b128 v[224:227], v145 offset:5120
	ds_read_b128 v[228:231], v145 offset:6144
	ds_read_b128 v[232:235], v145 offset:7168
	global_load_lds_dwordx4 v[140:141], off
	v_lshl_add_u64 v[140:141], s[50:51], 0, v[138:139]
	s_add_i32 m0, s58, 0xe000
	s_nop 0
	global_load_lds_dwordx4 v[140:141], off
	s_waitcnt vmcnt(8)
	s_waitcnt lgkmcnt(0)
	s_barrier
	s_setprio 1
	s_waitcnt lgkmcnt(0)
	v_mfma_f32_16x16x32_bf16 v[126:129], v[146:149], v[200:203], 0
	v_mfma_f32_16x16x32_bf16 v[122:125], v[154:157], v[200:203], 0
	v_mfma_f32_16x16x32_bf16 v[110:113], v[146:149], v[212:215], 0
	v_mfma_f32_16x16x32_bf16 v[106:109], v[154:157], v[212:215], 0
	v_mfma_f32_16x16x32_bf16 v[94:97], v[146:149], v[220:223], 0
	v_mfma_f32_16x16x32_bf16 v[90:93], v[154:157], v[220:223], 0
	v_mfma_f32_16x16x32_bf16 v[78:81], v[146:149], v[228:231], 0
	v_mfma_f32_16x16x32_bf16 v[74:77], v[154:157], v[228:231], 0
	v_mfma_f32_16x16x32_bf16 v[126:129], v[150:153], v[208:211], v[126:129]
	v_mfma_f32_16x16x32_bf16 v[122:125], v[158:161], v[208:211], v[122:125]
	v_mfma_f32_16x16x32_bf16 v[110:113], v[150:153], v[216:219], v[110:113]
	v_mfma_f32_16x16x32_bf16 v[106:109], v[158:161], v[216:219], v[106:109]
	v_mfma_f32_16x16x32_bf16 v[94:97], v[150:153], v[224:227], v[94:97]
	v_mfma_f32_16x16x32_bf16 v[90:93], v[158:161], v[224:227], v[90:93]
	v_mfma_f32_16x16x32_bf16 v[78:81], v[150:153], v[232:235], v[78:81]
	v_mfma_f32_16x16x32_bf16 v[74:77], v[158:161], v[232:235], v[74:77]
	s_setprio 0
	s_setprio 1
	v_mfma_f32_16x16x32_bf16 v[118:121], v[174:177], v[200:203], 0
	v_mfma_f32_16x16x32_bf16 v[114:117], v[182:185], v[200:203], 0
	v_mfma_f32_16x16x32_bf16 v[102:105], v[174:177], v[212:215], 0
	v_mfma_f32_16x16x32_bf16 v[98:101], v[182:185], v[212:215], 0
	v_mfma_f32_16x16x32_bf16 v[86:89], v[174:177], v[220:223], 0
	v_mfma_f32_16x16x32_bf16 v[82:85], v[182:185], v[220:223], 0
	v_mfma_f32_16x16x32_bf16 v[70:73], v[174:177], v[228:231], 0
	v_mfma_f32_16x16x32_bf16 v[66:69], v[182:185], v[228:231], 0
	v_mfma_f32_16x16x32_bf16 v[118:121], v[178:181], v[208:211], v[118:121]
	v_mfma_f32_16x16x32_bf16 v[114:117], v[186:189], v[208:211], v[114:117]
	v_mfma_f32_16x16x32_bf16 v[102:105], v[178:181], v[216:219], v[102:105]
	v_mfma_f32_16x16x32_bf16 v[98:101], v[186:189], v[216:219], v[98:101]
	v_mfma_f32_16x16x32_bf16 v[86:89], v[178:181], v[224:227], v[86:89]
	v_mfma_f32_16x16x32_bf16 v[82:85], v[186:189], v[224:227], v[82:85]
	v_mfma_f32_16x16x32_bf16 v[70:73], v[178:181], v[232:235], v[70:73]
	v_mfma_f32_16x16x32_bf16 v[66:69], v[186:189], v[232:235], v[66:69]
	s_setprio 0
	s_barrier
	s_add_i32 s70, s70, s57
	v_lshl_add_u64 v[140:141], s[52:53], 0, v[0:1]
	s_mov_b32 m0, s70
	ds_read_b128 v[200:203], v145 offset:16384
	ds_read_b128 v[208:211], v145 offset:17408
	ds_read_b128 v[212:215], v145 offset:18432
	ds_read_b128 v[216:219], v145 offset:19456
	ds_read_b128 v[220:223], v145 offset:20480
	ds_read_b128 v[224:227], v145 offset:21504
	ds_read_b128 v[228:231], v145 offset:22528
	ds_read_b128 v[232:235], v145 offset:23552
	global_load_lds_dwordx4 v[140:141], off
	s_add_i32 m0, s70, 0x2000
	s_add_u32 s70, s52, 0x40000
	v_lshl_add_u64 v[190:191], s[52:53], 0, v[130:131]
	s_addc_u32 s71, s53, 0
	s_add_i32 vcc_hi, vcc_hi, s57
	global_load_lds_dwordx4 v[190:191], off
	v_lshl_add_u64 v[236:237], s[70:71], 0, v[0:1]
	s_mov_b32 m0, vcc_hi
	v_lshl_add_u64 v[238:239], s[54:55], 0, v[132:133]
	global_load_lds_dwordx4 v[236:237], off
	v_lshl_add_u64 v[236:237], s[70:71], 0, v[130:131]
	s_add_i32 m0, vcc_hi, 0x2000
	s_nop 0
	global_load_lds_dwordx4 v[236:237], off
	v_lshl_add_u64 v[236:237], s[54:55], 0, v[134:135]
	s_mov_b32 m0, s58
	s_nop 0
	global_load_lds_dwordx4 v[236:237], off
	s_mov_b32 m0, s59
	s_nop 0
	global_load_lds_dwordx4 v[238:239], off
	s_waitcnt vmcnt(8)
	s_waitcnt lgkmcnt(0)
	s_barrier
; #define PG8_STAGEA(bufoff, gbase, voff) do { _Pragma("unroll") for (int _i = 0; _i < 2; ++_i) \
;         __builtin_amdgcn_global_load_lds((const unsigned*)((const char*)(gbase) + (voff)[_i]), (PG8_LAS unsigned*)(lds + (bufoff) + ldsw + _i * 8192), 16, 0, A_AUX); } while (0)
; #define PG8_LDA(dst, b, h) do { _Pragma("unroll") for (int m = 0; m < 4; ++m) _Pragma("unroll") for (int k = 0; k < 2; ++k) dst[m][k] = *(const PG8_LAS bf16x8*)(lds + PG8_SA(b, h) + aoff + m * 2048 + k * 1024); } while (0)
; #define PG8_LDB(dst, b, h) do { _Pragma("unroll") for (int n = 0; n < 2; ++n) _Pragma("unroll") for (int k = 0; k < 2; ++k) dst[n][k] = *(const PG8_LAS bf16x8*)(lds + PG8_SB(b, h) + boff + n * 2048 + k * 1024); } while (0)
; #define PG8_MMA(ai, bj, At, Bt) do { __builtin_amdgcn_s_setprio(1); _Pragma("unroll") for (int m = 0; m < 4; ++m) _Pragma("unroll") for (int n = 0; n < 2; ++n) _Pragma("unroll") for (int k = 0; k < 2; ++k) \
;         acc[ai][bj][m][n] = __builtin_amdgcn_mfma_f32_16x16x32_bf16(Bt[n][k], At[m][k], acc[ai][bj][m][n], 0, 0, 0); __builtin_amdgcn_s_setprio(0); } while (0)
; #define PG8_WAIT_V(n) asm volatile("s_waitcnt vmcnt(" #n ")" ::: "memory")
; #define PG8_WAIT_L(n) asm volatile("s_waitcnt lgkmcnt(" #n ")" ::: "memory")
; #define PG8_BAR __builtin_amdgcn_s_barrier()
; #define PG8_SCHED __builtin_amdgcn_sched_barrier(0)
;     ...
;             PG8_WAIT_V(8); PG8_WAIT_L(0); PG8_BAR; PG8_MMA(1, 0, At, B0); PG8_MMA(1, 1, At, B1); PG8_BAR; PG8_SCHED;
;             PG8_LDB(B0, 1, 0); PG8_LDB(B1, 1, 1); PG8_SCHED; PG8_LDA(At, 1, 0); PG8_STAGEA(PG8_SA(0, 1), a2 + hstep, voffA);
;             PG8_WAIT_V(8); PG8_WAIT_L(0); PG8_BAR; PG8_MMA(0, 0, At, B0); PG8_MMA(0, 1, At, B1); PG8_BAR; PG8_SCHED;
	s_setprio 1
	s_waitcnt lgkmcnt(0)
	v_mfma_f32_16x16x32_bf16 v[62:65], v[146:149], v[200:203], 0
	v_mfma_f32_16x16x32_bf16 v[58:61], v[154:157], v[200:203], 0
	v_mfma_f32_16x16x32_bf16 v[46:49], v[146:149], v[212:215], 0
	v_mfma_f32_16x16x32_bf16 v[42:45], v[154:157], v[212:215], 0
	v_mfma_f32_16x16x32_bf16 v[30:33], v[146:149], v[220:223], 0
	v_mfma_f32_16x16x32_bf16 v[26:29], v[154:157], v[220:223], 0
	v_mfma_f32_16x16x32_bf16 v[14:17], v[146:149], v[228:231], 0
	v_mfma_f32_16x16x32_bf16 v[10:13], v[154:157], v[228:231], 0
	v_mfma_f32_16x16x32_bf16 v[62:65], v[150:153], v[208:211], v[62:65]
	v_mfma_f32_16x16x32_bf16 v[58:61], v[158:161], v[208:211], v[58:61]
	v_mfma_f32_16x16x32_bf16 v[46:49], v[150:153], v[216:219], v[46:49]
	v_mfma_f32_16x16x32_bf16 v[42:45], v[158:161], v[216:219], v[42:45]
	v_mfma_f32_16x16x32_bf16 v[30:33], v[150:153], v[224:227], v[30:33]
	v_mfma_f32_16x16x32_bf16 v[26:29], v[158:161], v[224:227], v[26:29]
	v_mfma_f32_16x16x32_bf16 v[14:17], v[150:153], v[232:235], v[14:17]
	v_mfma_f32_16x16x32_bf16 v[10:13], v[158:161], v[232:235], v[10:13]
	s_setprio 0
	s_setprio 1
	v_mfma_f32_16x16x32_bf16 v[54:57], v[174:177], v[200:203], 0
	v_mfma_f32_16x16x32_bf16 v[50:53], v[182:185], v[200:203], 0
	v_mfma_f32_16x16x32_bf16 v[38:41], v[174:177], v[212:215], 0
	v_mfma_f32_16x16x32_bf16 v[34:37], v[182:185], v[212:215], 0
	v_mfma_f32_16x16x32_bf16 v[22:25], v[174:177], v[220:223], 0
	v_mfma_f32_16x16x32_bf16 v[18:21], v[182:185], v[220:223], 0
	v_mfma_f32_16x16x32_bf16 v[6:9], v[174:177], v[228:231], 0
	v_mfma_f32_16x16x32_bf16 v[2:5], v[182:185], v[228:231], 0
	v_mfma_f32_16x16x32_bf16 v[54:57], v[178:181], v[208:211], v[54:57]
	v_mfma_f32_16x16x32_bf16 v[50:53], v[186:189], v[208:211], v[50:53]
	v_mfma_f32_16x16x32_bf16 v[38:41], v[178:181], v[216:219], v[38:41]
	v_mfma_f32_16x16x32_bf16 v[34:37], v[186:189], v[216:219], v[34:37]
	v_mfma_f32_16x16x32_bf16 v[22:25], v[178:181], v[224:227], v[22:25]
	v_mfma_f32_16x16x32_bf16 v[18:21], v[186:189], v[224:227], v[18:21]
	v_mfma_f32_16x16x32_bf16 v[6:9], v[178:181], v[232:235], v[6:9]
	v_mfma_f32_16x16x32_bf16 v[2:5], v[186:189], v[232:235], v[2:5]
	s_setprio 0
	s_barrier
	s_add_i32 s70, 0, 0x18000
	s_add_i32 s71, 0, 0x1c000
	v_add_u32_e32 v158, s70, v143
	v_add_u32_e32 v186, s71, v143
	ds_read_b128 v[146:149], v158
	ds_read_b128 v[150:153], v158 offset:1024
	ds_read_b128 v[154:157], v158 offset:2048
	ds_read_b128 v[158:161], v158 offset:3072
	ds_read_b128 v[174:177], v186
	ds_read_b128 v[178:181], v186 offset:1024
	ds_read_b128 v[182:185], v186 offset:2048
	ds_read_b128 v[186:189], v186 offset:3072
	s_add_u32 s54, s54, 0x40000
	s_addc_u32 s55, s55, 0
	s_mov_b32 m0, s60
	v_lshl_add_u64 v[240:241], s[54:55], 0, v[134:135]
	ds_read_b128 v[200:203], v145 offset:32768
	ds_read_b128 v[208:211], v145 offset:33792
	ds_read_b128 v[212:215], v145 offset:34816
	ds_read_b128 v[216:219], v145 offset:35840
	ds_read_b128 v[220:223], v145 offset:36864
	ds_read_b128 v[224:227], v145 offset:37888
	ds_read_b128 v[228:231], v145 offset:38912
	ds_read_b128 v[232:235], v145 offset:39936
	global_load_lds_dwordx4 v[240:241], off
	v_lshl_add_u64 v[240:241], s[54:55], 0, v[132:133]
	s_mov_b32 m0, s61
	s_nop 0
	global_load_lds_dwordx4 v[240:241], off
	s_waitcnt vmcnt(8)
	s_waitcnt lgkmcnt(0)
	s_barrier
	s_setprio 1
	s_waitcnt lgkmcnt(0)
	v_mfma_f32_16x16x32_bf16 v[126:129], v[146:149], v[200:203], v[126:129]
	v_mfma_f32_16x16x32_bf16 v[122:125], v[154:157], v[200:203], v[122:125]
	v_mfma_f32_16x16x32_bf16 v[110:113], v[146:149], v[212:215], v[110:113]
	v_mfma_f32_16x16x32_bf16 v[106:109], v[154:157], v[212:215], v[106:109]
	v_mfma_f32_16x16x32_bf16 v[94:97], v[146:149], v[220:223], v[94:97]
	v_mfma_f32_16x16x32_bf16 v[90:93], v[154:157], v[220:223], v[90:93]
	v_mfma_f32_16x16x32_bf16 v[78:81], v[146:149], v[228:231], v[78:81]
	v_mfma_f32_16x16x32_bf16 v[74:77], v[154:157], v[228:231], v[74:77]
	v_mfma_f32_16x16x32_bf16 v[126:129], v[150:153], v[208:211], v[126:129]
	v_mfma_f32_16x16x32_bf16 v[122:125], v[158:161], v[208:211], v[122:125]
	v_mfma_f32_16x16x32_bf16 v[110:113], v[150:153], v[216:219], v[110:113]
	v_mfma_f32_16x16x32_bf16 v[106:109], v[158:161], v[216:219], v[106:109]
	v_mfma_f32_16x16x32_bf16 v[94:97], v[150:153], v[224:227], v[94:97]
	v_mfma_f32_16x16x32_bf16 v[90:93], v[158:161], v[224:227], v[90:93]
	v_mfma_f32_16x16x32_bf16 v[78:81], v[150:153], v[232:235], v[78:81]
	v_mfma_f32_16x16x32_bf16 v[74:77], v[158:161], v[232:235], v[74:77]
	s_setprio 0
	s_setprio 1
	v_mfma_f32_16x16x32_bf16 v[118:121], v[174:177], v[200:203], v[118:121]
	v_mfma_f32_16x16x32_bf16 v[114:117], v[182:185], v[200:203], v[114:117]
	v_mfma_f32_16x16x32_bf16 v[102:105], v[174:177], v[212:215], v[102:105]
	v_mfma_f32_16x16x32_bf16 v[98:101], v[182:185], v[212:215], v[98:101]
	v_mfma_f32_16x16x32_bf16 v[86:89], v[174:177], v[220:223], v[86:89]
	v_mfma_f32_16x16x32_bf16 v[82:85], v[182:185], v[220:223], v[82:85]
	v_mfma_f32_16x16x32_bf16 v[70:73], v[174:177], v[228:231], v[70:73]
	v_mfma_f32_16x16x32_bf16 v[66:69], v[182:185], v[228:231], v[66:69]
	v_mfma_f32_16x16x32_bf16 v[118:121], v[178:181], v[208:211], v[118:121]
	v_mfma_f32_16x16x32_bf16 v[114:117], v[186:189], v[208:211], v[114:117]
	v_mfma_f32_16x16x32_bf16 v[102:105], v[178:181], v[216:219], v[102:105]
	v_mfma_f32_16x16x32_bf16 v[98:101], v[186:189], v[216:219], v[98:101]
	v_mfma_f32_16x16x32_bf16 v[86:89], v[178:181], v[224:227], v[86:89]
	v_mfma_f32_16x16x32_bf16 v[82:85], v[186:189], v[224:227], v[82:85]
	v_mfma_f32_16x16x32_bf16 v[70:73], v[178:181], v[232:235], v[70:73]
	v_mfma_f32_16x16x32_bf16 v[66:69], v[186:189], v[232:235], v[66:69]
	s_setprio 0
	s_barrier
; #define PG8_STAGE(bufoff, gbase, voff) do { _Pragma("unroll") for (int _i = 0; _i < 2; ++_i) \
;         __builtin_amdgcn_global_load_lds((const unsigned*)((const char*)(gbase) + (voff)[_i]), (PG8_LAS unsigned*)(lds + (bufoff) + ldsw + _i * 8192), 16, 0, 0); } while (0)
; #define PG8_STAGEA(bufoff, gbase, voff) do { _Pragma("unroll") for (int _i = 0; _i < 2; ++_i) \
;         __builtin_amdgcn_global_load_lds((const unsigned*)((const char*)(gbase) + (voff)[_i]), (PG8_LAS unsigned*)(lds + (bufoff) + ldsw + _i * 8192), 16, 0, A_AUX); } while (0)
; #define PG8_LDA(dst, b, h) do { _Pragma("unroll") for (int m = 0; m < 4; ++m) _Pragma("unroll") for (int k = 0; k < 2; ++k) dst[m][k] = *(const PG8_LAS bf16x8*)(lds + PG8_SA(b, h) + aoff + m * 2048 + k * 1024); } while (0)
; #define PG8_MMA(ai, bj, At, Bt) do { __builtin_amdgcn_s_setprio(1); _Pragma("unroll") for (int m = 0; m < 4; ++m) _Pragma("unroll") for (int n = 0; n < 2; ++n) _Pragma("unroll") for (int k = 0; k < 2; ++k) \
;         acc[ai][bj][m][n] = __builtin_amdgcn_mfma_f32_16x16x32_bf16(Bt[n][k], At[m][k], acc[ai][bj][m][n], 0, 0, 0); __builtin_amdgcn_s_setprio(0); } while (0)
; #define PG8_WAIT_V(n) asm volatile("s_waitcnt vmcnt(" #n ")" ::: "memory")
; #define PG8_WAIT_L(n) asm volatile("s_waitcnt lgkmcnt(" #n ")" ::: "memory")
; #define PG8_BAR __builtin_amdgcn_s_barrier()
; #define PG8_SCHED __builtin_amdgcn_sched_barrier(0)
;     ...
;         for (int t = 0; t < nt; t += 2) {
;     ...
;             PG8_LDA(At, 1, 1); PG8_STAGE(PG8_SB(1, 0), b3, voffB); PG8_STAGE(PG8_SB(1, 1), b3 + hstep, voffB); PG8_STAGEA(PG8_SA(1, 0), a3, voffA);
;             PG8_WAIT_V(8); PG8_WAIT_L(0); PG8_BAR; PG8_MMA(1, 0, At, B0); PG8_MMA(1, 1, At, B1); PG8_BAR; PG8_SCHED;
	s_add_i32 s54, s70, s57
	v_lshl_add_u64 v[140:141], v[140:141], 0, s[8:9]
	s_mov_b32 m0, s54
	ds_read_b128 v[200:203], v145 offset:49152
	ds_read_b128 v[208:211], v145 offset:50176
	ds_read_b128 v[212:215], v145 offset:51200
	ds_read_b128 v[216:219], v145 offset:52224
	ds_read_b128 v[220:223], v145 offset:53248
	ds_read_b128 v[224:227], v145 offset:54272
	ds_read_b128 v[228:231], v145 offset:55296
	ds_read_b128 v[232:235], v145 offset:56320
	global_load_lds_dwordx4 v[140:141], off
	s_add_i32 m0, s54, 0x2000
	s_add_u32 s52, s52, 0x40080
	v_lshl_add_u64 v[140:141], v[190:191], 0, s[8:9]
	s_addc_u32 s53, s53, 0
	s_add_i32 s54, s71, s57
	global_load_lds_dwordx4 v[140:141], off
	v_lshl_add_u64 v[140:141], s[52:53], 0, v[0:1]
	s_mov_b32 m0, s54
	s_nop 0
	global_load_lds_dwordx4 v[140:141], off
	v_lshl_add_u64 v[140:141], s[52:53], 0, v[130:131]
	s_add_i32 m0, s54, 0x2000
	s_nop 0
	global_load_lds_dwordx4 v[140:141], off
	v_lshl_add_u64 v[140:141], v[236:237], 0, s[8:9]
	s_mov_b32 m0, s62
	s_nop 0
	global_load_lds_dwordx4 v[140:141], off
	v_lshl_add_u64 v[140:141], v[238:239], 0, s[8:9]
	s_mov_b32 m0, s63
	s_nop 0
	global_load_lds_dwordx4 v[140:141], off
	s_waitcnt vmcnt(8)
	s_waitcnt lgkmcnt(0)
	s_barrier
	s_setprio 1
	s_waitcnt lgkmcnt(0)
	v_mfma_f32_16x16x32_bf16 v[62:65], v[146:149], v[200:203], v[62:65]
	v_mfma_f32_16x16x32_bf16 v[58:61], v[154:157], v[200:203], v[58:61]
	v_mfma_f32_16x16x32_bf16 v[46:49], v[146:149], v[212:215], v[46:49]
	v_mfma_f32_16x16x32_bf16 v[42:45], v[154:157], v[212:215], v[42:45]
	v_mfma_f32_16x16x32_bf16 v[30:33], v[146:149], v[220:223], v[30:33]
	v_mfma_f32_16x16x32_bf16 v[26:29], v[154:157], v[220:223], v[26:29]
	v_mfma_f32_16x16x32_bf16 v[14:17], v[146:149], v[228:231], v[14:17]
	v_mfma_f32_16x16x32_bf16 v[10:13], v[154:157], v[228:231], v[10:13]
	v_mfma_f32_16x16x32_bf16 v[62:65], v[150:153], v[208:211], v[62:65]
	v_mfma_f32_16x16x32_bf16 v[58:61], v[158:161], v[208:211], v[58:61]
	v_mfma_f32_16x16x32_bf16 v[46:49], v[150:153], v[216:219], v[46:49]
	v_mfma_f32_16x16x32_bf16 v[42:45], v[158:161], v[216:219], v[42:45]
	v_mfma_f32_16x16x32_bf16 v[30:33], v[150:153], v[224:227], v[30:33]
	v_mfma_f32_16x16x32_bf16 v[26:29], v[158:161], v[224:227], v[26:29]
	v_mfma_f32_16x16x32_bf16 v[14:17], v[150:153], v[232:235], v[14:17]
	v_mfma_f32_16x16x32_bf16 v[10:13], v[158:161], v[232:235], v[10:13]
	s_setprio 0
	s_setprio 1
	v_mfma_f32_16x16x32_bf16 v[54:57], v[174:177], v[200:203], v[54:57]
	v_mfma_f32_16x16x32_bf16 v[50:53], v[182:185], v[200:203], v[50:53]
	v_mfma_f32_16x16x32_bf16 v[38:41], v[174:177], v[212:215], v[38:41]
	v_mfma_f32_16x16x32_bf16 v[34:37], v[182:185], v[212:215], v[34:37]
	v_mfma_f32_16x16x32_bf16 v[22:25], v[174:177], v[220:223], v[22:25]
	v_mfma_f32_16x16x32_bf16 v[18:21], v[182:185], v[220:223], v[18:21]
	v_mfma_f32_16x16x32_bf16 v[6:9], v[174:177], v[228:231], v[6:9]
	v_mfma_f32_16x16x32_bf16 v[2:5], v[182:185], v[228:231], v[2:5]
	v_mfma_f32_16x16x32_bf16 v[54:57], v[178:181], v[208:211], v[54:57]
	v_mfma_f32_16x16x32_bf16 v[50:53], v[186:189], v[208:211], v[50:53]
	v_mfma_f32_16x16x32_bf16 v[38:41], v[178:181], v[216:219], v[38:41]
	v_mfma_f32_16x16x32_bf16 v[34:37], v[186:189], v[216:219], v[34:37]
	v_mfma_f32_16x16x32_bf16 v[22:25], v[178:181], v[224:227], v[22:25]
	v_mfma_f32_16x16x32_bf16 v[18:21], v[186:189], v[224:227], v[18:21]
	v_mfma_f32_16x16x32_bf16 v[6:9], v[178:181], v[232:235], v[6:9]
	v_mfma_f32_16x16x32_bf16 v[2:5], v[186:189], v[232:235], v[2:5]
	s_setprio 0
	s_barrier
	s_add_i32 vcc_lo, vcc_lo, 2
	s_add_u32 s50, s50, 0x100
	s_addc_u32 s51, s51, 0
	s_add_u32 s73, s73, 0x100
	s_addc_u32 s76, s76, 0
